# loop-edge edit in the gate_up / in_proj / down K-loops: tail increments + head selects issued inside the last MFMA block, back edge re-enters after the scalar prefix
# speedup vs baseline: 1.0031x; 1.0031x over previous
.LBB0_98:
	s_add_u32 s18, s44, 0xfffc0080
	s_addc_u32 s19, s45, -1
	s_add_i32 s46, 0, 0x10000
	s_cmp_eq_u32 s15, 12
	s_cselect_b32 s25, s7, s19
	s_cselect_b32 s24, s10, s18
	s_cselect_b32 s23, s5, s14
	s_cselect_b32 s22, s11, s13
	s_add_i32 s47, 0, 0x14000
.Lrot_98:
	ds_read_b128 v[156:159], v240
	ds_read_b128 v[160:163], v240 offset:1024
	ds_read_b128 v[164:167], v240 offset:2048
	ds_read_b128 v[168:171], v240 offset:3072
	ds_read_b128 v[172:175], v240 offset:16384
	ds_read_b128 v[176:179], v240 offset:17408
	ds_read_b128 v[180:183], v240 offset:18432
	ds_read_b128 v[184:187], v240 offset:19456
	s_add_i32 m0, s29, 0xc000
	ds_read_b128 v[208:211], v155
	ds_read_b128 v[212:215], v155 offset:1024
	ds_read_b128 v[216:219], v155 offset:2048
	ds_read_b128 v[220:223], v155 offset:3072
	ds_read_b128 v[224:227], v155 offset:4096
	ds_read_b128 v[228:231], v155 offset:5120
	ds_read_b128 v[232:235], v155 offset:6144
	ds_read_b128 v[236:239], v155 offset:7168
	global_load_lds_dwordx4 v144, s[44:45]
	s_add_i32 m0, s29, 0xe000
	s_nop 0
	global_load_lds_dwordx4 v146, s[44:45]
	s_waitcnt vmcnt(8)
	s_waitcnt lgkmcnt(0)
	s_barrier
	s_setprio 1
	s_waitcnt lgkmcnt(0)
	v_mfma_f32_16x16x32_bf16 v[128:131], v[156:159], v[208:211], v[128:131]
	v_mfma_f32_16x16x32_bf16 v[120:123], v[164:167], v[208:211], v[120:123]
	v_mfma_f32_16x16x32_bf16 v[112:115], v[156:159], v[216:219], v[112:115]
	v_mfma_f32_16x16x32_bf16 v[104:107], v[164:167], v[216:219], v[104:107]
	v_mfma_f32_16x16x32_bf16 v[96:99], v[156:159], v[224:227], v[96:99]
	v_mfma_f32_16x16x32_bf16 v[88:91], v[164:167], v[224:227], v[88:91]
	v_mfma_f32_16x16x32_bf16 v[80:83], v[156:159], v[232:235], v[80:83]
	v_mfma_f32_16x16x32_bf16 v[72:75], v[164:167], v[232:235], v[72:75]
	v_mfma_f32_16x16x32_bf16 v[128:131], v[160:163], v[212:215], v[128:131]
	v_mfma_f32_16x16x32_bf16 v[120:123], v[168:171], v[212:215], v[120:123]
	v_mfma_f32_16x16x32_bf16 v[112:115], v[160:163], v[220:223], v[112:115]
	v_mfma_f32_16x16x32_bf16 v[104:107], v[168:171], v[220:223], v[104:107]
	v_mfma_f32_16x16x32_bf16 v[96:99], v[160:163], v[228:231], v[96:99]
	v_mfma_f32_16x16x32_bf16 v[88:91], v[168:171], v[228:231], v[88:91]
	v_mfma_f32_16x16x32_bf16 v[80:83], v[160:163], v[236:239], v[80:83]
	v_mfma_f32_16x16x32_bf16 v[72:75], v[168:171], v[236:239], v[72:75]
	s_setprio 0
	s_setprio 1
	v_mfma_f32_16x16x32_bf16 v[124:127], v[172:175], v[208:211], v[124:127]
	v_mfma_f32_16x16x32_bf16 v[116:119], v[180:183], v[208:211], v[116:119]
	v_mfma_f32_16x16x32_bf16 v[108:111], v[172:175], v[216:219], v[108:111]
	v_mfma_f32_16x16x32_bf16 v[100:103], v[180:183], v[216:219], v[100:103]
	v_mfma_f32_16x16x32_bf16 v[92:95], v[172:175], v[224:227], v[92:95]
	v_mfma_f32_16x16x32_bf16 v[84:87], v[180:183], v[224:227], v[84:87]
	v_mfma_f32_16x16x32_bf16 v[76:79], v[172:175], v[232:235], v[76:79]
	v_mfma_f32_16x16x32_bf16 v[68:71], v[180:183], v[232:235], v[68:71]
	v_mfma_f32_16x16x32_bf16 v[124:127], v[176:179], v[212:215], v[124:127]
	v_mfma_f32_16x16x32_bf16 v[116:119], v[184:187], v[212:215], v[116:119]
	v_mfma_f32_16x16x32_bf16 v[108:111], v[176:179], v[220:223], v[108:111]
	v_mfma_f32_16x16x32_bf16 v[100:103], v[184:187], v[220:223], v[100:103]
	v_mfma_f32_16x16x32_bf16 v[92:95], v[176:179], v[228:231], v[92:95]
	v_mfma_f32_16x16x32_bf16 v[84:87], v[184:187], v[228:231], v[84:87]
	v_mfma_f32_16x16x32_bf16 v[76:79], v[176:179], v[236:239], v[76:79]
	v_mfma_f32_16x16x32_bf16 v[68:71], v[184:187], v[236:239], v[68:71]
	s_setprio 0
	s_barrier
	s_add_i32 s18, s46, s28
	s_mov_b32 m0, s18
	ds_read_b128 v[208:211], v155 offset:16384
	ds_read_b128 v[212:215], v155 offset:17408
	ds_read_b128 v[216:219], v155 offset:18432
	ds_read_b128 v[220:223], v155 offset:19456
	ds_read_b128 v[224:227], v155 offset:20480
	ds_read_b128 v[228:231], v155 offset:21504
	ds_read_b128 v[232:235], v155 offset:22528
	ds_read_b128 v[236:239], v155 offset:23552
	global_load_lds_dwordx4 v2, s[22:23]
	s_add_i32 m0, s18, 0x2000
	s_add_u32 s18, s22, 0x40000
	s_addc_u32 s19, s23, 0
	s_add_i32 s46, s47, s28
	global_load_lds_dwordx4 v142, s[22:23]
	s_mov_b32 m0, s46
	s_nop 0
	global_load_lds_dwordx4 v2, s[18:19]
	s_add_i32 m0, s46, 0x2000
	s_nop 0
	global_load_lds_dwordx4 v142, s[18:19]
	s_mov_b32 m0, s29
	s_nop 0
	global_load_lds_dwordx4 v0, s[24:25]
	s_mov_b32 m0, s43
	s_nop 0
	global_load_lds_dwordx4 v140, s[24:25]
	s_waitcnt vmcnt(8)
	s_waitcnt lgkmcnt(0)
	s_barrier
	s_setprio 1
	s_waitcnt lgkmcnt(0)
	v_mfma_f32_16x16x32_bf16 v[64:67], v[156:159], v[208:211], v[64:67]
	v_mfma_f32_16x16x32_bf16 v[56:59], v[164:167], v[208:211], v[56:59]
	v_mfma_f32_16x16x32_bf16 v[48:51], v[156:159], v[216:219], v[48:51]
	v_mfma_f32_16x16x32_bf16 v[40:43], v[164:167], v[216:219], v[40:43]
	v_mfma_f32_16x16x32_bf16 v[32:35], v[156:159], v[224:227], v[32:35]
	v_mfma_f32_16x16x32_bf16 v[24:27], v[164:167], v[224:227], v[24:27]
	v_mfma_f32_16x16x32_bf16 v[16:19], v[156:159], v[232:235], v[16:19]
	v_mfma_f32_16x16x32_bf16 v[8:11], v[164:167], v[232:235], v[8:11]
	v_mfma_f32_16x16x32_bf16 v[64:67], v[160:163], v[212:215], v[64:67]
	v_mfma_f32_16x16x32_bf16 v[56:59], v[168:171], v[212:215], v[56:59]
	v_mfma_f32_16x16x32_bf16 v[48:51], v[160:163], v[220:223], v[48:51]
	v_mfma_f32_16x16x32_bf16 v[40:43], v[168:171], v[220:223], v[40:43]
	v_mfma_f32_16x16x32_bf16 v[32:35], v[160:163], v[228:231], v[32:35]
	v_mfma_f32_16x16x32_bf16 v[24:27], v[168:171], v[228:231], v[24:27]
	v_mfma_f32_16x16x32_bf16 v[16:19], v[160:163], v[236:239], v[16:19]
	v_mfma_f32_16x16x32_bf16 v[8:11], v[168:171], v[236:239], v[8:11]
	s_setprio 0
	s_setprio 1
	v_mfma_f32_16x16x32_bf16 v[60:63], v[172:175], v[208:211], v[60:63]
	v_mfma_f32_16x16x32_bf16 v[52:55], v[180:183], v[208:211], v[52:55]
	v_mfma_f32_16x16x32_bf16 v[44:47], v[172:175], v[216:219], v[44:47]
	v_mfma_f32_16x16x32_bf16 v[36:39], v[180:183], v[216:219], v[36:39]
	v_mfma_f32_16x16x32_bf16 v[28:31], v[172:175], v[224:227], v[28:31]
	v_mfma_f32_16x16x32_bf16 v[20:23], v[180:183], v[224:227], v[20:23]
	v_mfma_f32_16x16x32_bf16 v[12:15], v[172:175], v[232:235], v[12:15]
	v_mfma_f32_16x16x32_bf16 v[4:7], v[180:183], v[232:235], v[4:7]
	v_mfma_f32_16x16x32_bf16 v[60:63], v[176:179], v[212:215], v[60:63]
	v_mfma_f32_16x16x32_bf16 v[52:55], v[184:187], v[212:215], v[52:55]
	v_mfma_f32_16x16x32_bf16 v[44:47], v[176:179], v[220:223], v[44:47]
	v_mfma_f32_16x16x32_bf16 v[36:39], v[184:187], v[220:223], v[36:39]
	v_mfma_f32_16x16x32_bf16 v[28:31], v[176:179], v[228:231], v[28:31]
	v_mfma_f32_16x16x32_bf16 v[20:23], v[184:187], v[228:231], v[20:23]
	v_mfma_f32_16x16x32_bf16 v[12:15], v[176:179], v[236:239], v[12:15]
	v_mfma_f32_16x16x32_bf16 v[4:7], v[184:187], v[236:239], v[4:7]
	s_setprio 0
	s_barrier
	s_add_i32 s46, 0, 0x18000
	s_add_i32 s47, 0, 0x1c000
	ds_read_b128 v[156:159], v240 offset:32768
	ds_read_b128 v[160:163], v240 offset:33792
	ds_read_b128 v[164:167], v240 offset:34816
	ds_read_b128 v[168:171], v240 offset:35840
	ds_read_b128 v[172:175], v240 offset:49152
	ds_read_b128 v[176:179], v240 offset:50176
	ds_read_b128 v[180:183], v240 offset:51200
	ds_read_b128 v[184:187], v240 offset:52224
	s_add_u32 s18, s24, 0x40000
	s_addc_u32 s19, s25, 0
	s_mov_b32 m0, s48
	ds_read_b128 v[208:211], v155 offset:32768
	ds_read_b128 v[212:215], v155 offset:33792
	ds_read_b128 v[216:219], v155 offset:34816
	ds_read_b128 v[220:223], v155 offset:35840
	ds_read_b128 v[224:227], v155 offset:36864
	ds_read_b128 v[228:231], v155 offset:37888
	ds_read_b128 v[232:235], v155 offset:38912
	ds_read_b128 v[236:239], v155 offset:39936
	global_load_lds_dwordx4 v0, s[18:19]
	s_mov_b32 m0, s49
	s_nop 0
	global_load_lds_dwordx4 v140, s[18:19]
	s_waitcnt vmcnt(8)
	s_waitcnt lgkmcnt(0)
	s_barrier
	s_setprio 1
	s_waitcnt lgkmcnt(0)
	v_mfma_f32_16x16x32_bf16 v[128:131], v[156:159], v[208:211], v[128:131]
	v_mfma_f32_16x16x32_bf16 v[120:123], v[164:167], v[208:211], v[120:123]
	v_mfma_f32_16x16x32_bf16 v[112:115], v[156:159], v[216:219], v[112:115]
	v_mfma_f32_16x16x32_bf16 v[104:107], v[164:167], v[216:219], v[104:107]
	v_mfma_f32_16x16x32_bf16 v[96:99], v[156:159], v[224:227], v[96:99]
	v_mfma_f32_16x16x32_bf16 v[88:91], v[164:167], v[224:227], v[88:91]
	v_mfma_f32_16x16x32_bf16 v[80:83], v[156:159], v[232:235], v[80:83]
	v_mfma_f32_16x16x32_bf16 v[72:75], v[164:167], v[232:235], v[72:75]
	v_mfma_f32_16x16x32_bf16 v[128:131], v[160:163], v[212:215], v[128:131]
	v_mfma_f32_16x16x32_bf16 v[120:123], v[168:171], v[212:215], v[120:123]
	v_mfma_f32_16x16x32_bf16 v[112:115], v[160:163], v[220:223], v[112:115]
	v_mfma_f32_16x16x32_bf16 v[104:107], v[168:171], v[220:223], v[104:107]
	v_mfma_f32_16x16x32_bf16 v[96:99], v[160:163], v[228:231], v[96:99]
	v_mfma_f32_16x16x32_bf16 v[88:91], v[168:171], v[228:231], v[88:91]
	v_mfma_f32_16x16x32_bf16 v[80:83], v[160:163], v[236:239], v[80:83]
	v_mfma_f32_16x16x32_bf16 v[72:75], v[168:171], v[236:239], v[72:75]
	s_setprio 0
	s_setprio 1
	v_mfma_f32_16x16x32_bf16 v[124:127], v[172:175], v[208:211], v[124:127]
	v_mfma_f32_16x16x32_bf16 v[116:119], v[180:183], v[208:211], v[116:119]
	v_mfma_f32_16x16x32_bf16 v[108:111], v[172:175], v[216:219], v[108:111]
	v_mfma_f32_16x16x32_bf16 v[100:103], v[180:183], v[216:219], v[100:103]
	v_mfma_f32_16x16x32_bf16 v[92:95], v[172:175], v[224:227], v[92:95]
	v_mfma_f32_16x16x32_bf16 v[84:87], v[180:183], v[224:227], v[84:87]
	v_mfma_f32_16x16x32_bf16 v[76:79], v[172:175], v[232:235], v[76:79]
	v_mfma_f32_16x16x32_bf16 v[68:71], v[180:183], v[232:235], v[68:71]
	v_mfma_f32_16x16x32_bf16 v[124:127], v[176:179], v[212:215], v[124:127]
	v_mfma_f32_16x16x32_bf16 v[116:119], v[184:187], v[212:215], v[116:119]
	v_mfma_f32_16x16x32_bf16 v[108:111], v[176:179], v[220:223], v[108:111]
	v_mfma_f32_16x16x32_bf16 v[100:103], v[184:187], v[220:223], v[100:103]
	v_mfma_f32_16x16x32_bf16 v[92:95], v[176:179], v[228:231], v[92:95]
	v_mfma_f32_16x16x32_bf16 v[84:87], v[184:187], v[228:231], v[84:87]
	v_mfma_f32_16x16x32_bf16 v[76:79], v[176:179], v[236:239], v[76:79]
	v_mfma_f32_16x16x32_bf16 v[68:71], v[184:187], v[236:239], v[68:71]
	s_setprio 0
	s_barrier
	s_add_i32 s18, s46, s28
	s_add_u32 s100, s22, 0x80
	s_addc_u32 s101, s23, 0
	s_mov_b32 m0, s18
	ds_read_b128 v[208:211], v155 offset:49152
	ds_read_b128 v[212:215], v155 offset:50176
	ds_read_b128 v[216:219], v155 offset:51200
	ds_read_b128 v[220:223], v155 offset:52224
	ds_read_b128 v[224:227], v155 offset:53248
	ds_read_b128 v[228:231], v155 offset:54272
	ds_read_b128 v[232:235], v155 offset:55296
	ds_read_b128 v[236:239], v155 offset:56320
	global_load_lds_dwordx4 v2, s[100:101]
	s_add_i32 m0, s18, 0x2000
	s_add_u32 s18, s22, 0x40080
	s_addc_u32 s19, s23, 0
	s_add_i32 s22, s47, s28
	global_load_lds_dwordx4 v142, s[100:101]
	s_mov_b32 m0, s22
	s_nop 0
	global_load_lds_dwordx4 v2, s[18:19]
	s_add_i32 m0, s22, 0x2000
	s_nop 0
	global_load_lds_dwordx4 v142, s[18:19]
	s_add_u32 s100, s24, 0x80
	s_addc_u32 s101, s25, 0
	s_mov_b32 m0, s50
	s_nop 0
	global_load_lds_dwordx4 v0, s[100:101]
	s_mov_b32 m0, s51
	s_nop 0
	global_load_lds_dwordx4 v140, s[100:101]
	s_waitcnt vmcnt(8)
	s_waitcnt lgkmcnt(0)
	s_barrier
	s_setprio 1
	s_waitcnt lgkmcnt(0)
	v_mfma_f32_16x16x32_bf16 v[64:67], v[156:159], v[208:211], v[64:67]
	v_mfma_f32_16x16x32_bf16 v[56:59], v[164:167], v[208:211], v[56:59]
	v_mfma_f32_16x16x32_bf16 v[48:51], v[156:159], v[216:219], v[48:51]
	v_mfma_f32_16x16x32_bf16 v[40:43], v[164:167], v[216:219], v[40:43]
	v_mfma_f32_16x16x32_bf16 v[32:35], v[156:159], v[224:227], v[32:35]
	v_mfma_f32_16x16x32_bf16 v[24:27], v[164:167], v[224:227], v[24:27]
	v_mfma_f32_16x16x32_bf16 v[16:19], v[156:159], v[232:235], v[16:19]
	v_mfma_f32_16x16x32_bf16 v[8:11], v[164:167], v[232:235], v[8:11]
	v_mfma_f32_16x16x32_bf16 v[64:67], v[160:163], v[212:215], v[64:67]
	v_mfma_f32_16x16x32_bf16 v[56:59], v[168:171], v[212:215], v[56:59]
	v_mfma_f32_16x16x32_bf16 v[48:51], v[160:163], v[220:223], v[48:51]
	v_mfma_f32_16x16x32_bf16 v[40:43], v[168:171], v[220:223], v[40:43]
	v_mfma_f32_16x16x32_bf16 v[32:35], v[160:163], v[228:231], v[32:35]
	v_mfma_f32_16x16x32_bf16 v[24:27], v[168:171], v[228:231], v[24:27]
	v_mfma_f32_16x16x32_bf16 v[16:19], v[160:163], v[236:239], v[16:19]
	v_mfma_f32_16x16x32_bf16 v[8:11], v[168:171], v[236:239], v[8:11]
	s_setprio 0
	s_add_i32 s15, s15, 2
	s_add_u32 s44, s44, 0x100
	s_addc_u32 s45, s45, 0
	s_add_u32 s13, s13, 0x100
	s_addc_u32 s14, s14, 0
	s_add_u32 s18, s44, 0xfffc0080
	s_addc_u32 s19, s45, -1
	s_add_i32 s46, 0, 0x10000
	s_cmp_eq_u32 s15, 12
	s_cselect_b32 s25, s7, s19
	s_cselect_b32 s24, s10, s18
	s_cselect_b32 s23, s5, s14
	s_cselect_b32 s22, s11, s13
	s_add_i32 s47, 0, 0x14000
	s_setprio 1
	v_mfma_f32_16x16x32_bf16 v[60:63], v[172:175], v[208:211], v[60:63]
	v_mfma_f32_16x16x32_bf16 v[52:55], v[180:183], v[208:211], v[52:55]
	v_mfma_f32_16x16x32_bf16 v[44:47], v[172:175], v[216:219], v[44:47]
	v_mfma_f32_16x16x32_bf16 v[36:39], v[180:183], v[216:219], v[36:39]
	v_mfma_f32_16x16x32_bf16 v[28:31], v[172:175], v[224:227], v[28:31]
	v_mfma_f32_16x16x32_bf16 v[20:23], v[180:183], v[224:227], v[20:23]
	v_mfma_f32_16x16x32_bf16 v[12:15], v[172:175], v[232:235], v[12:15]
	v_mfma_f32_16x16x32_bf16 v[4:7], v[180:183], v[232:235], v[4:7]
	v_mfma_f32_16x16x32_bf16 v[60:63], v[176:179], v[212:215], v[60:63]
	v_mfma_f32_16x16x32_bf16 v[52:55], v[184:187], v[212:215], v[52:55]
	v_mfma_f32_16x16x32_bf16 v[44:47], v[176:179], v[220:223], v[44:47]
	v_mfma_f32_16x16x32_bf16 v[36:39], v[184:187], v[220:223], v[36:39]
	v_mfma_f32_16x16x32_bf16 v[28:31], v[176:179], v[228:231], v[28:31]
	v_mfma_f32_16x16x32_bf16 v[20:23], v[184:187], v[228:231], v[20:23]
	v_mfma_f32_16x16x32_bf16 v[12:15], v[176:179], v[236:239], v[12:15]
	v_mfma_f32_16x16x32_bf16 v[4:7], v[184:187], v[236:239], v[4:7]
	s_setprio 0
	s_barrier
	s_cmp_gt_u32 s15, 13
	s_cbranch_scc0 .Lrot_98
	s_lshl_b32 s5, s42, 8
	s_and_b64 vcc, exec, s[2:3]
	s_cbranch_vccz .LBB0_101
	v_or_b32_e32 v148, s5, v152
	v_ashrrev_i32_e32 v149, 31, v148
	v_readlane_b32 s10, v255, 11
	v_lshlrev_b64 v[148:149], 6, v[148:149]
	v_readlane_b32 s11, v255, 12
	s_nop 1
	v_lshl_add_u64 v[148:149], s[10:11], 0, v[148:149]
	global_load_dwordx4 v[156:159], v[148:149], off
	global_load_dwordx4 v[160:163], v[148:149], off offset:32
	global_load_dwordx4 v[164:167], v[148:149], off offset:16
	global_load_dwordx4 v[168:171], v[148:149], off offset:48
	s_barrier

.Lrot_811:
	ds_read_b128 v[144:147], v213
	ds_read_b128 v[148:151], v213 offset:1024
	ds_read_b128 v[152:155], v213 offset:2048
	ds_read_b128 v[156:159], v213 offset:3072
	ds_read_b128 v[160:163], v213 offset:16384
	ds_read_b128 v[164:167], v213 offset:17408
	ds_read_b128 v[168:171], v213 offset:18432
	ds_read_b128 v[172:175], v213 offset:19456
	s_add_i32 m0, s47, 0xc000
	ds_read_b128 v[176:179], v212
	ds_read_b128 v[180:183], v212 offset:1024
	ds_read_b128 v[184:187], v212 offset:2048
	ds_read_b128 v[214:217], v212 offset:3072
	ds_read_b128 v[218:221], v212 offset:4096
	ds_read_b128 v[222:225], v212 offset:5120
	ds_read_b128 v[226:229], v212 offset:6144
	ds_read_b128 v[230:233], v212 offset:7168
	global_load_lds_dwordx4 v140, s[44:45]
	s_add_i32 m0, s47, 0xe000
	s_nop 0
	global_load_lds_dwordx4 v142, s[44:45]
	s_waitcnt vmcnt(8)
	s_waitcnt lgkmcnt(0)
	s_barrier
	s_setprio 1
	s_waitcnt lgkmcnt(0)
	v_mfma_f32_16x16x32_bf16 v[128:131], v[144:147], v[176:179], v[128:131]
	v_mfma_f32_16x16x32_bf16 v[124:127], v[152:155], v[176:179], v[124:127]
	v_mfma_f32_16x16x32_bf16 v[112:115], v[144:147], v[184:187], v[112:115]
	v_mfma_f32_16x16x32_bf16 v[108:111], v[152:155], v[184:187], v[108:111]
	v_mfma_f32_16x16x32_bf16 v[96:99], v[144:147], v[218:221], v[96:99]
	v_mfma_f32_16x16x32_bf16 v[92:95], v[152:155], v[218:221], v[92:95]
	v_mfma_f32_16x16x32_bf16 v[80:83], v[144:147], v[226:229], v[80:83]
	v_mfma_f32_16x16x32_bf16 v[76:79], v[152:155], v[226:229], v[76:79]
	v_mfma_f32_16x16x32_bf16 v[128:131], v[148:151], v[180:183], v[128:131]
	v_mfma_f32_16x16x32_bf16 v[124:127], v[156:159], v[180:183], v[124:127]
	v_mfma_f32_16x16x32_bf16 v[112:115], v[148:151], v[214:217], v[112:115]
	v_mfma_f32_16x16x32_bf16 v[108:111], v[156:159], v[214:217], v[108:111]
	v_mfma_f32_16x16x32_bf16 v[96:99], v[148:151], v[222:225], v[96:99]
	v_mfma_f32_16x16x32_bf16 v[92:95], v[156:159], v[222:225], v[92:95]
	v_mfma_f32_16x16x32_bf16 v[80:83], v[148:151], v[230:233], v[80:83]
	v_mfma_f32_16x16x32_bf16 v[76:79], v[156:159], v[230:233], v[76:79]
	s_setprio 0
	s_setprio 1
	v_mfma_f32_16x16x32_bf16 v[120:123], v[160:163], v[176:179], v[120:123]
	v_mfma_f32_16x16x32_bf16 v[116:119], v[168:171], v[176:179], v[116:119]
	v_mfma_f32_16x16x32_bf16 v[104:107], v[160:163], v[184:187], v[104:107]
	v_mfma_f32_16x16x32_bf16 v[100:103], v[168:171], v[184:187], v[100:103]
	v_mfma_f32_16x16x32_bf16 v[88:91], v[160:163], v[218:221], v[88:91]
	v_mfma_f32_16x16x32_bf16 v[84:87], v[168:171], v[218:221], v[84:87]
	v_mfma_f32_16x16x32_bf16 v[72:75], v[160:163], v[226:229], v[72:75]
	v_mfma_f32_16x16x32_bf16 v[68:71], v[168:171], v[226:229], v[68:71]
	v_mfma_f32_16x16x32_bf16 v[120:123], v[164:167], v[180:183], v[120:123]
	v_mfma_f32_16x16x32_bf16 v[116:119], v[172:175], v[180:183], v[116:119]
	v_mfma_f32_16x16x32_bf16 v[104:107], v[164:167], v[214:217], v[104:107]
	v_mfma_f32_16x16x32_bf16 v[100:103], v[172:175], v[214:217], v[100:103]
	v_mfma_f32_16x16x32_bf16 v[88:91], v[164:167], v[222:225], v[88:91]
	v_mfma_f32_16x16x32_bf16 v[84:87], v[172:175], v[222:225], v[84:87]
	v_mfma_f32_16x16x32_bf16 v[72:75], v[164:167], v[230:233], v[72:75]
	v_mfma_f32_16x16x32_bf16 v[68:71], v[172:175], v[230:233], v[68:71]
	s_setprio 0
	s_barrier
	s_add_i32 s18, s18, s46
	s_mov_b32 m0, s18
	ds_read_b128 v[176:179], v212 offset:16384
	ds_read_b128 v[180:183], v212 offset:17408
	ds_read_b128 v[184:187], v212 offset:18432
	ds_read_b128 v[214:217], v212 offset:19456
	ds_read_b128 v[218:221], v212 offset:20480
	ds_read_b128 v[222:225], v212 offset:21504
	ds_read_b128 v[226:229], v212 offset:22528
	ds_read_b128 v[230:233], v212 offset:23552
	global_load_lds_dwordx4 v2, s[22:23]
	s_add_i32 m0, s18, 0x2000
	s_add_u32 s18, s22, 0xb0000
	s_addc_u32 s19, s23, 0
	s_add_i32 s44, s62, s46
	global_load_lds_dwordx4 v0, s[22:23]
	s_mov_b32 m0, s44
	s_nop 0
	global_load_lds_dwordx4 v2, s[18:19]
	s_add_i32 m0, s44, 0x2000
	s_nop 0
	global_load_lds_dwordx4 v0, s[18:19]
	s_mov_b32 m0, s47
	s_nop 0
	global_load_lds_dwordx4 v2, s[24:25]
	s_mov_b32 m0, s48
	s_nop 0
	global_load_lds_dwordx4 v0, s[24:25]
	s_waitcnt vmcnt(8)
	s_waitcnt lgkmcnt(0)
	s_barrier
	s_setprio 1
	s_waitcnt lgkmcnt(0)
	v_mfma_f32_16x16x32_bf16 v[64:67], v[144:147], v[176:179], v[64:67]
	v_mfma_f32_16x16x32_bf16 v[60:63], v[152:155], v[176:179], v[60:63]
	v_mfma_f32_16x16x32_bf16 v[48:51], v[144:147], v[184:187], v[48:51]
	v_mfma_f32_16x16x32_bf16 v[44:47], v[152:155], v[184:187], v[44:47]
	v_mfma_f32_16x16x32_bf16 v[32:35], v[144:147], v[218:221], v[32:35]
	v_mfma_f32_16x16x32_bf16 v[28:31], v[152:155], v[218:221], v[28:31]
	v_mfma_f32_16x16x32_bf16 v[16:19], v[144:147], v[226:229], v[16:19]
	v_mfma_f32_16x16x32_bf16 v[12:15], v[152:155], v[226:229], v[12:15]
	v_mfma_f32_16x16x32_bf16 v[64:67], v[148:151], v[180:183], v[64:67]
	v_mfma_f32_16x16x32_bf16 v[60:63], v[156:159], v[180:183], v[60:63]
	v_mfma_f32_16x16x32_bf16 v[48:51], v[148:151], v[214:217], v[48:51]
	v_mfma_f32_16x16x32_bf16 v[44:47], v[156:159], v[214:217], v[44:47]
	v_mfma_f32_16x16x32_bf16 v[32:35], v[148:151], v[222:225], v[32:35]
	v_mfma_f32_16x16x32_bf16 v[28:31], v[156:159], v[222:225], v[28:31]
	v_mfma_f32_16x16x32_bf16 v[16:19], v[148:151], v[230:233], v[16:19]
	v_mfma_f32_16x16x32_bf16 v[12:15], v[156:159], v[230:233], v[12:15]
	s_setprio 0
	s_setprio 1
	v_mfma_f32_16x16x32_bf16 v[56:59], v[160:163], v[176:179], v[56:59]
	v_mfma_f32_16x16x32_bf16 v[52:55], v[168:171], v[176:179], v[52:55]
	v_mfma_f32_16x16x32_bf16 v[40:43], v[160:163], v[184:187], v[40:43]
	v_mfma_f32_16x16x32_bf16 v[36:39], v[168:171], v[184:187], v[36:39]
	v_mfma_f32_16x16x32_bf16 v[24:27], v[160:163], v[218:221], v[24:27]
	v_mfma_f32_16x16x32_bf16 v[20:23], v[168:171], v[218:221], v[20:23]
	v_mfma_f32_16x16x32_bf16 v[8:11], v[160:163], v[226:229], v[8:11]
	v_mfma_f32_16x16x32_bf16 v[4:7], v[168:171], v[226:229], v[4:7]
	v_mfma_f32_16x16x32_bf16 v[56:59], v[164:167], v[180:183], v[56:59]
	v_mfma_f32_16x16x32_bf16 v[52:55], v[172:175], v[180:183], v[52:55]
	v_mfma_f32_16x16x32_bf16 v[40:43], v[164:167], v[214:217], v[40:43]
	v_mfma_f32_16x16x32_bf16 v[36:39], v[172:175], v[214:217], v[36:39]
	v_mfma_f32_16x16x32_bf16 v[24:27], v[164:167], v[222:225], v[24:27]
	v_mfma_f32_16x16x32_bf16 v[20:23], v[172:175], v[222:225], v[20:23]
	v_mfma_f32_16x16x32_bf16 v[8:11], v[164:167], v[230:233], v[8:11]
	v_mfma_f32_16x16x32_bf16 v[4:7], v[172:175], v[230:233], v[4:7]
	s_setprio 0
	s_barrier
	s_add_i32 s44, 0, 0x18000
	s_add_i32 s45, 0, 0x1c000
	ds_read_b128 v[144:147], v213 offset:32768
	ds_read_b128 v[148:151], v213 offset:33792
	ds_read_b128 v[152:155], v213 offset:34816
	ds_read_b128 v[156:159], v213 offset:35840
	ds_read_b128 v[160:163], v213 offset:49152
	ds_read_b128 v[164:167], v213 offset:50176
	ds_read_b128 v[168:171], v213 offset:51200
	ds_read_b128 v[172:175], v213 offset:52224
	s_add_u32 s18, s24, 0xb0000
	s_addc_u32 s19, s25, 0
	s_mov_b32 m0, s49
	ds_read_b128 v[176:179], v212 offset:32768
	ds_read_b128 v[180:183], v212 offset:33792
	ds_read_b128 v[184:187], v212 offset:34816
	ds_read_b128 v[214:217], v212 offset:35840
	ds_read_b128 v[218:221], v212 offset:36864
	ds_read_b128 v[222:225], v212 offset:37888
	ds_read_b128 v[226:229], v212 offset:38912
	ds_read_b128 v[230:233], v212 offset:39936
	global_load_lds_dwordx4 v2, s[18:19]
	s_mov_b32 m0, s50
	s_nop 0
	global_load_lds_dwordx4 v0, s[18:19]
	s_waitcnt vmcnt(8)
	s_waitcnt lgkmcnt(0)
	s_barrier
	s_setprio 1
	s_waitcnt lgkmcnt(0)
	v_mfma_f32_16x16x32_bf16 v[128:131], v[144:147], v[176:179], v[128:131]
	v_mfma_f32_16x16x32_bf16 v[124:127], v[152:155], v[176:179], v[124:127]
	v_mfma_f32_16x16x32_bf16 v[112:115], v[144:147], v[184:187], v[112:115]
	v_mfma_f32_16x16x32_bf16 v[108:111], v[152:155], v[184:187], v[108:111]
	v_mfma_f32_16x16x32_bf16 v[96:99], v[144:147], v[218:221], v[96:99]
	v_mfma_f32_16x16x32_bf16 v[92:95], v[152:155], v[218:221], v[92:95]
	v_mfma_f32_16x16x32_bf16 v[80:83], v[144:147], v[226:229], v[80:83]
	v_mfma_f32_16x16x32_bf16 v[76:79], v[152:155], v[226:229], v[76:79]
	v_mfma_f32_16x16x32_bf16 v[128:131], v[148:151], v[180:183], v[128:131]
	v_mfma_f32_16x16x32_bf16 v[124:127], v[156:159], v[180:183], v[124:127]
	v_mfma_f32_16x16x32_bf16 v[112:115], v[148:151], v[214:217], v[112:115]
	v_mfma_f32_16x16x32_bf16 v[108:111], v[156:159], v[214:217], v[108:111]
	v_mfma_f32_16x16x32_bf16 v[96:99], v[148:151], v[222:225], v[96:99]
	v_mfma_f32_16x16x32_bf16 v[92:95], v[156:159], v[222:225], v[92:95]
	v_mfma_f32_16x16x32_bf16 v[80:83], v[148:151], v[230:233], v[80:83]
	v_mfma_f32_16x16x32_bf16 v[76:79], v[156:159], v[230:233], v[76:79]
	s_setprio 0
	s_setprio 1
	v_mfma_f32_16x16x32_bf16 v[120:123], v[160:163], v[176:179], v[120:123]
	v_mfma_f32_16x16x32_bf16 v[116:119], v[168:171], v[176:179], v[116:119]
	v_mfma_f32_16x16x32_bf16 v[104:107], v[160:163], v[184:187], v[104:107]
	v_mfma_f32_16x16x32_bf16 v[100:103], v[168:171], v[184:187], v[100:103]
	v_mfma_f32_16x16x32_bf16 v[88:91], v[160:163], v[218:221], v[88:91]
	v_mfma_f32_16x16x32_bf16 v[84:87], v[168:171], v[218:221], v[84:87]
	v_mfma_f32_16x16x32_bf16 v[72:75], v[160:163], v[226:229], v[72:75]
	v_mfma_f32_16x16x32_bf16 v[68:71], v[168:171], v[226:229], v[68:71]
	v_mfma_f32_16x16x32_bf16 v[120:123], v[164:167], v[180:183], v[120:123]
	v_mfma_f32_16x16x32_bf16 v[116:119], v[172:175], v[180:183], v[116:119]
	v_mfma_f32_16x16x32_bf16 v[104:107], v[164:167], v[214:217], v[104:107]
	v_mfma_f32_16x16x32_bf16 v[100:103], v[172:175], v[214:217], v[100:103]
	v_mfma_f32_16x16x32_bf16 v[88:91], v[164:167], v[222:225], v[88:91]
	v_mfma_f32_16x16x32_bf16 v[84:87], v[172:175], v[222:225], v[84:87]
	v_mfma_f32_16x16x32_bf16 v[72:75], v[164:167], v[230:233], v[72:75]
	v_mfma_f32_16x16x32_bf16 v[68:71], v[172:175], v[230:233], v[68:71]
	s_setprio 0
	s_barrier
	s_add_i32 s18, s44, s46
	s_add_u32 s100, s22, 0x80
	s_addc_u32 s101, s23, 0
	s_mov_b32 m0, s18
	ds_read_b128 v[176:179], v212 offset:49152
	ds_read_b128 v[180:183], v212 offset:50176
	ds_read_b128 v[184:187], v212 offset:51200
	ds_read_b128 v[214:217], v212 offset:52224
	ds_read_b128 v[218:221], v212 offset:53248
	ds_read_b128 v[222:225], v212 offset:54272
	ds_read_b128 v[226:229], v212 offset:55296
	ds_read_b128 v[230:233], v212 offset:56320
	global_load_lds_dwordx4 v2, s[100:101]
	s_add_i32 m0, s18, 0x2000
	s_add_u32 s18, s22, 0xb0080
	s_addc_u32 s19, s23, 0
	s_add_i32 s22, s45, s46
	global_load_lds_dwordx4 v0, s[100:101]
	s_mov_b32 m0, s22
	s_nop 0
	global_load_lds_dwordx4 v2, s[18:19]
	s_add_i32 m0, s22, 0x2000
	s_nop 0
	global_load_lds_dwordx4 v0, s[18:19]
	s_add_u32 s100, s24, 0x80
	s_addc_u32 s101, s25, 0
	s_mov_b32 m0, s52
	s_nop 0
	global_load_lds_dwordx4 v2, s[100:101]
	s_mov_b32 m0, s53
	s_nop 0
	global_load_lds_dwordx4 v0, s[100:101]
	s_waitcnt vmcnt(8)
	s_waitcnt lgkmcnt(0)
	s_barrier
	s_setprio 1
	s_waitcnt lgkmcnt(0)
	v_mfma_f32_16x16x32_bf16 v[64:67], v[144:147], v[176:179], v[64:67]
	v_mfma_f32_16x16x32_bf16 v[60:63], v[152:155], v[176:179], v[60:63]
	v_mfma_f32_16x16x32_bf16 v[48:51], v[144:147], v[184:187], v[48:51]
	v_mfma_f32_16x16x32_bf16 v[44:47], v[152:155], v[184:187], v[44:47]
	v_mfma_f32_16x16x32_bf16 v[32:35], v[144:147], v[218:221], v[32:35]
	v_mfma_f32_16x16x32_bf16 v[28:31], v[152:155], v[218:221], v[28:31]
	v_mfma_f32_16x16x32_bf16 v[16:19], v[144:147], v[226:229], v[16:19]
	v_mfma_f32_16x16x32_bf16 v[12:15], v[152:155], v[226:229], v[12:15]
	v_mfma_f32_16x16x32_bf16 v[64:67], v[148:151], v[180:183], v[64:67]
	v_mfma_f32_16x16x32_bf16 v[60:63], v[156:159], v[180:183], v[60:63]
	v_mfma_f32_16x16x32_bf16 v[48:51], v[148:151], v[214:217], v[48:51]
	v_mfma_f32_16x16x32_bf16 v[44:47], v[156:159], v[214:217], v[44:47]
	v_mfma_f32_16x16x32_bf16 v[32:35], v[148:151], v[222:225], v[32:35]
	v_mfma_f32_16x16x32_bf16 v[28:31], v[156:159], v[222:225], v[28:31]
	v_mfma_f32_16x16x32_bf16 v[16:19], v[148:151], v[230:233], v[16:19]
	v_mfma_f32_16x16x32_bf16 v[12:15], v[156:159], v[230:233], v[12:15]
	s_setprio 0
	s_add_i32 s15, s15, 2
	s_add_u32 s13, s13, 0x100
	s_addc_u32 s14, s14, 0
	s_mov_b64 s[44:45], s[42:43]
	s_add_u32 s42, s44, 0x100
	s_addc_u32 s43, s45, 0
	s_add_i32 s18, 0, 0x10000
	s_cmp_eq_u32 s15, 40
	s_cselect_b32 s25, s11, s43
	s_cselect_b32 s24, s10, s42
	s_cselect_b32 s23, s17, s14
	s_cselect_b32 s22, s16, s13
	s_add_i32 s62, 0, 0x14000
	s_setprio 1
	v_mfma_f32_16x16x32_bf16 v[56:59], v[160:163], v[176:179], v[56:59]
	v_mfma_f32_16x16x32_bf16 v[52:55], v[168:171], v[176:179], v[52:55]
	v_mfma_f32_16x16x32_bf16 v[40:43], v[160:163], v[184:187], v[40:43]
	v_mfma_f32_16x16x32_bf16 v[36:39], v[168:171], v[184:187], v[36:39]
	v_mfma_f32_16x16x32_bf16 v[24:27], v[160:163], v[218:221], v[24:27]
	v_mfma_f32_16x16x32_bf16 v[20:23], v[168:171], v[218:221], v[20:23]
	v_mfma_f32_16x16x32_bf16 v[8:11], v[160:163], v[226:229], v[8:11]
	v_mfma_f32_16x16x32_bf16 v[4:7], v[168:171], v[226:229], v[4:7]
	v_mfma_f32_16x16x32_bf16 v[56:59], v[164:167], v[180:183], v[56:59]
	v_mfma_f32_16x16x32_bf16 v[52:55], v[172:175], v[180:183], v[52:55]
	v_mfma_f32_16x16x32_bf16 v[40:43], v[164:167], v[214:217], v[40:43]
	v_mfma_f32_16x16x32_bf16 v[36:39], v[172:175], v[214:217], v[36:39]
	v_mfma_f32_16x16x32_bf16 v[24:27], v[164:167], v[222:225], v[24:27]
	v_mfma_f32_16x16x32_bf16 v[20:23], v[172:175], v[222:225], v[20:23]
	v_mfma_f32_16x16x32_bf16 v[8:11], v[164:167], v[230:233], v[8:11]
	v_mfma_f32_16x16x32_bf16 v[4:7], v[172:175], v[230:233], v[4:7]
	s_setprio 0
	s_barrier
	s_cmp_gt_u32 s15, 41
	s_cbranch_scc0 .Lrot_811
	s_and_b64 vcc, exec, s[4:5]
	s_cbranch_vccz .LBB0_814
	s_barrier

.Lrot_928:
	ds_read_b128 v[148:151], v246
	ds_read_b128 v[158:161], v246 offset:1024
	ds_read_b128 v[162:165], v246 offset:2048
	ds_read_b128 v[166:169], v246 offset:3072
	ds_read_b128 v[170:173], v246 offset:16384
	ds_read_b128 v[174:177], v246 offset:17408
	ds_read_b128 v[178:181], v246 offset:18432
	ds_read_b128 v[182:185], v246 offset:19456
	s_add_i32 m0, s29, 0xc000
	ds_read_b128 v[186:189], v157
	ds_read_b128 v[208:211], v157 offset:1024
	ds_read_b128 v[212:215], v157 offset:2048
	ds_read_b128 v[216:219], v157 offset:3072
	ds_read_b128 v[220:223], v157 offset:4096
	ds_read_b128 v[224:227], v157 offset:5120
	ds_read_b128 v[228:231], v157 offset:6144
	ds_read_b128 v[232:235], v157 offset:7168
	global_load_lds_dwordx4 v144, s[40:41]
	s_add_i32 m0, s29, 0xe000
	s_nop 0
	global_load_lds_dwordx4 v146, s[40:41]
	s_waitcnt vmcnt(8)
	s_waitcnt lgkmcnt(0)
	s_barrier
	s_setprio 1
	s_waitcnt lgkmcnt(0)
	v_mfma_f32_16x16x32_bf16 v[128:131], v[148:151], v[186:189], v[128:131]
	v_mfma_f32_16x16x32_bf16 v[124:127], v[162:165], v[186:189], v[124:127]
	v_mfma_f32_16x16x32_bf16 v[116:119], v[148:151], v[212:215], v[116:119]
	v_mfma_f32_16x16x32_bf16 v[108:111], v[162:165], v[212:215], v[108:111]
	v_mfma_f32_16x16x32_bf16 v[100:103], v[148:151], v[220:223], v[100:103]
	v_mfma_f32_16x16x32_bf16 v[92:95], v[162:165], v[220:223], v[92:95]
	v_mfma_f32_16x16x32_bf16 v[84:87], v[148:151], v[228:231], v[84:87]
	v_mfma_f32_16x16x32_bf16 v[76:79], v[162:165], v[228:231], v[76:79]
	v_mfma_f32_16x16x32_bf16 v[128:131], v[158:161], v[208:211], v[128:131]
	v_mfma_f32_16x16x32_bf16 v[124:127], v[166:169], v[208:211], v[124:127]
	v_mfma_f32_16x16x32_bf16 v[116:119], v[158:161], v[216:219], v[116:119]
	v_mfma_f32_16x16x32_bf16 v[108:111], v[166:169], v[216:219], v[108:111]
	v_mfma_f32_16x16x32_bf16 v[100:103], v[158:161], v[224:227], v[100:103]
	v_mfma_f32_16x16x32_bf16 v[92:95], v[166:169], v[224:227], v[92:95]
	v_mfma_f32_16x16x32_bf16 v[84:87], v[158:161], v[232:235], v[84:87]
	v_mfma_f32_16x16x32_bf16 v[76:79], v[166:169], v[232:235], v[76:79]
	s_setprio 0
	s_setprio 1
	v_mfma_f32_16x16x32_bf16 v[120:123], v[170:173], v[186:189], v[120:123]
	v_mfma_f32_16x16x32_bf16 v[112:115], v[178:181], v[186:189], v[112:115]
	v_mfma_f32_16x16x32_bf16 v[104:107], v[170:173], v[212:215], v[104:107]
	v_mfma_f32_16x16x32_bf16 v[96:99], v[178:181], v[212:215], v[96:99]
	v_mfma_f32_16x16x32_bf16 v[88:91], v[170:173], v[220:223], v[88:91]
	v_mfma_f32_16x16x32_bf16 v[80:83], v[178:181], v[220:223], v[80:83]
	v_mfma_f32_16x16x32_bf16 v[72:75], v[170:173], v[228:231], v[72:75]
	v_mfma_f32_16x16x32_bf16 v[68:71], v[178:181], v[228:231], v[68:71]
	v_mfma_f32_16x16x32_bf16 v[120:123], v[174:177], v[208:211], v[120:123]
	v_mfma_f32_16x16x32_bf16 v[112:115], v[182:185], v[208:211], v[112:115]
	v_mfma_f32_16x16x32_bf16 v[104:107], v[174:177], v[216:219], v[104:107]
	v_mfma_f32_16x16x32_bf16 v[96:99], v[182:185], v[216:219], v[96:99]
	v_mfma_f32_16x16x32_bf16 v[88:91], v[174:177], v[224:227], v[88:91]
	v_mfma_f32_16x16x32_bf16 v[80:83], v[182:185], v[224:227], v[80:83]
	v_mfma_f32_16x16x32_bf16 v[72:75], v[174:177], v[232:235], v[72:75]
	v_mfma_f32_16x16x32_bf16 v[68:71], v[182:185], v[232:235], v[68:71]
	s_setprio 0
	s_barrier
	s_add_i32 s18, s52, s28
	s_mov_b32 m0, s18
	ds_read_b128 v[186:189], v157 offset:16384
	ds_read_b128 v[208:211], v157 offset:17408
	ds_read_b128 v[212:215], v157 offset:18432
	ds_read_b128 v[216:219], v157 offset:19456
	ds_read_b128 v[220:223], v157 offset:20480
	ds_read_b128 v[224:227], v157 offset:21504
	ds_read_b128 v[228:231], v157 offset:22528
	ds_read_b128 v[232:235], v157 offset:23552
	global_load_lds_dwordx4 v2, s[22:23]
	s_add_i32 m0, s18, 0x2000
	s_add_u32 s18, s22, 0x10000
	s_addc_u32 s19, s23, 0
	s_add_i32 s52, s53, s28
	global_load_lds_dwordx4 v142, s[22:23]
	s_mov_b32 m0, s52
	s_nop 0
	global_load_lds_dwordx4 v2, s[18:19]
	s_add_i32 m0, s52, 0x2000
	s_nop 0
	global_load_lds_dwordx4 v142, s[18:19]
	s_mov_b32 m0, s29
	s_nop 0
	global_load_lds_dwordx4 v0, s[24:25]
	s_mov_b32 m0, s44
	s_nop 0
	global_load_lds_dwordx4 v140, s[24:25]
	s_waitcnt vmcnt(8)
	s_waitcnt lgkmcnt(0)
	s_barrier
	s_setprio 1
	s_waitcnt lgkmcnt(0)
	v_mfma_f32_16x16x32_bf16 v[64:67], v[148:151], v[186:189], v[64:67]
	v_mfma_f32_16x16x32_bf16 v[60:63], v[162:165], v[186:189], v[60:63]
	v_mfma_f32_16x16x32_bf16 v[52:55], v[148:151], v[212:215], v[52:55]
	v_mfma_f32_16x16x32_bf16 v[44:47], v[162:165], v[212:215], v[44:47]
	v_mfma_f32_16x16x32_bf16 v[36:39], v[148:151], v[220:223], v[36:39]
	v_mfma_f32_16x16x32_bf16 v[28:31], v[162:165], v[220:223], v[28:31]
	v_mfma_f32_16x16x32_bf16 v[20:23], v[148:151], v[228:231], v[20:23]
	v_mfma_f32_16x16x32_bf16 v[12:15], v[162:165], v[228:231], v[12:15]
	v_mfma_f32_16x16x32_bf16 v[64:67], v[158:161], v[208:211], v[64:67]
	v_mfma_f32_16x16x32_bf16 v[60:63], v[166:169], v[208:211], v[60:63]
	v_mfma_f32_16x16x32_bf16 v[52:55], v[158:161], v[216:219], v[52:55]
	v_mfma_f32_16x16x32_bf16 v[44:47], v[166:169], v[216:219], v[44:47]
	v_mfma_f32_16x16x32_bf16 v[36:39], v[158:161], v[224:227], v[36:39]
	v_mfma_f32_16x16x32_bf16 v[28:31], v[166:169], v[224:227], v[28:31]
	v_mfma_f32_16x16x32_bf16 v[20:23], v[158:161], v[232:235], v[20:23]
	v_mfma_f32_16x16x32_bf16 v[12:15], v[166:169], v[232:235], v[12:15]
	s_setprio 0
	s_setprio 1
	v_mfma_f32_16x16x32_bf16 v[56:59], v[170:173], v[186:189], v[56:59]
	v_mfma_f32_16x16x32_bf16 v[48:51], v[178:181], v[186:189], v[48:51]
	v_mfma_f32_16x16x32_bf16 v[40:43], v[170:173], v[212:215], v[40:43]
	v_mfma_f32_16x16x32_bf16 v[32:35], v[178:181], v[212:215], v[32:35]
	v_mfma_f32_16x16x32_bf16 v[24:27], v[170:173], v[220:223], v[24:27]
	v_mfma_f32_16x16x32_bf16 v[16:19], v[178:181], v[220:223], v[16:19]
	v_mfma_f32_16x16x32_bf16 v[8:11], v[170:173], v[228:231], v[8:11]
	v_mfma_f32_16x16x32_bf16 v[4:7], v[178:181], v[228:231], v[4:7]
	v_mfma_f32_16x16x32_bf16 v[56:59], v[174:177], v[208:211], v[56:59]
	v_mfma_f32_16x16x32_bf16 v[48:51], v[182:185], v[208:211], v[48:51]
	v_mfma_f32_16x16x32_bf16 v[40:43], v[174:177], v[216:219], v[40:43]
	v_mfma_f32_16x16x32_bf16 v[32:35], v[182:185], v[216:219], v[32:35]
	v_mfma_f32_16x16x32_bf16 v[24:27], v[174:177], v[224:227], v[24:27]
	v_mfma_f32_16x16x32_bf16 v[16:19], v[182:185], v[224:227], v[16:19]
	v_mfma_f32_16x16x32_bf16 v[8:11], v[174:177], v[232:235], v[8:11]
	v_mfma_f32_16x16x32_bf16 v[4:7], v[182:185], v[232:235], v[4:7]
	s_setprio 0
	s_barrier
	s_add_i32 s52, 0, 0x18000
	s_add_i32 s53, 0, 0x1c000
	ds_read_b128 v[148:151], v246 offset:32768
	ds_read_b128 v[158:161], v246 offset:33792
	ds_read_b128 v[162:165], v246 offset:34816
	ds_read_b128 v[166:169], v246 offset:35840
	ds_read_b128 v[170:173], v246 offset:49152
	ds_read_b128 v[174:177], v246 offset:50176
	ds_read_b128 v[178:181], v246 offset:51200
	ds_read_b128 v[182:185], v246 offset:52224
	s_add_u32 s18, s24, 0x40000
	s_addc_u32 s19, s25, 0
	s_mov_b32 m0, s45
	ds_read_b128 v[186:189], v157 offset:32768
	ds_read_b128 v[208:211], v157 offset:33792
	ds_read_b128 v[212:215], v157 offset:34816
	ds_read_b128 v[216:219], v157 offset:35840
	ds_read_b128 v[220:223], v157 offset:36864
	ds_read_b128 v[224:227], v157 offset:37888
	ds_read_b128 v[228:231], v157 offset:38912
	ds_read_b128 v[232:235], v157 offset:39936
	global_load_lds_dwordx4 v0, s[18:19]
	s_mov_b32 m0, s46
	s_nop 0
	global_load_lds_dwordx4 v140, s[18:19]
	s_waitcnt vmcnt(8)
	s_waitcnt lgkmcnt(0)
	s_barrier
	s_setprio 1
	s_waitcnt lgkmcnt(0)
	v_mfma_f32_16x16x32_bf16 v[128:131], v[148:151], v[186:189], v[128:131]
	v_mfma_f32_16x16x32_bf16 v[124:127], v[162:165], v[186:189], v[124:127]
	v_mfma_f32_16x16x32_bf16 v[116:119], v[148:151], v[212:215], v[116:119]
	v_mfma_f32_16x16x32_bf16 v[108:111], v[162:165], v[212:215], v[108:111]
	v_mfma_f32_16x16x32_bf16 v[100:103], v[148:151], v[220:223], v[100:103]
	v_mfma_f32_16x16x32_bf16 v[92:95], v[162:165], v[220:223], v[92:95]
	v_mfma_f32_16x16x32_bf16 v[84:87], v[148:151], v[228:231], v[84:87]
	v_mfma_f32_16x16x32_bf16 v[76:79], v[162:165], v[228:231], v[76:79]
	v_mfma_f32_16x16x32_bf16 v[128:131], v[158:161], v[208:211], v[128:131]
	v_mfma_f32_16x16x32_bf16 v[124:127], v[166:169], v[208:211], v[124:127]
	v_mfma_f32_16x16x32_bf16 v[116:119], v[158:161], v[216:219], v[116:119]
	v_mfma_f32_16x16x32_bf16 v[108:111], v[166:169], v[216:219], v[108:111]
	v_mfma_f32_16x16x32_bf16 v[100:103], v[158:161], v[224:227], v[100:103]
	v_mfma_f32_16x16x32_bf16 v[92:95], v[166:169], v[224:227], v[92:95]
	v_mfma_f32_16x16x32_bf16 v[84:87], v[158:161], v[232:235], v[84:87]
	v_mfma_f32_16x16x32_bf16 v[76:79], v[166:169], v[232:235], v[76:79]
	s_setprio 0
	s_setprio 1
	v_mfma_f32_16x16x32_bf16 v[120:123], v[170:173], v[186:189], v[120:123]
	v_mfma_f32_16x16x32_bf16 v[112:115], v[178:181], v[186:189], v[112:115]
	v_mfma_f32_16x16x32_bf16 v[104:107], v[170:173], v[212:215], v[104:107]
	v_mfma_f32_16x16x32_bf16 v[96:99], v[178:181], v[212:215], v[96:99]
	v_mfma_f32_16x16x32_bf16 v[88:91], v[170:173], v[220:223], v[88:91]
	v_mfma_f32_16x16x32_bf16 v[80:83], v[178:181], v[220:223], v[80:83]
	v_mfma_f32_16x16x32_bf16 v[72:75], v[170:173], v[228:231], v[72:75]
	v_mfma_f32_16x16x32_bf16 v[68:71], v[178:181], v[228:231], v[68:71]
	v_mfma_f32_16x16x32_bf16 v[120:123], v[174:177], v[208:211], v[120:123]
	v_mfma_f32_16x16x32_bf16 v[112:115], v[182:185], v[208:211], v[112:115]
	v_mfma_f32_16x16x32_bf16 v[104:107], v[174:177], v[216:219], v[104:107]
	v_mfma_f32_16x16x32_bf16 v[96:99], v[182:185], v[216:219], v[96:99]
	v_mfma_f32_16x16x32_bf16 v[88:91], v[174:177], v[224:227], v[88:91]
	v_mfma_f32_16x16x32_bf16 v[80:83], v[182:185], v[224:227], v[80:83]
	v_mfma_f32_16x16x32_bf16 v[72:75], v[174:177], v[232:235], v[72:75]
	v_mfma_f32_16x16x32_bf16 v[68:71], v[182:185], v[232:235], v[68:71]
	s_setprio 0
	s_barrier
	s_add_i32 s18, s52, s28
	s_add_u32 s100, s22, 0x80
	s_addc_u32 s101, s23, 0
	s_mov_b32 m0, s18
	ds_read_b128 v[186:189], v157 offset:49152
	ds_read_b128 v[208:211], v157 offset:50176
	ds_read_b128 v[212:215], v157 offset:51200
	ds_read_b128 v[216:219], v157 offset:52224
	ds_read_b128 v[220:223], v157 offset:53248
	ds_read_b128 v[224:227], v157 offset:54272
	ds_read_b128 v[228:231], v157 offset:55296
	ds_read_b128 v[232:235], v157 offset:56320
	global_load_lds_dwordx4 v2, s[100:101]
	s_add_i32 m0, s18, 0x2000
	s_add_u32 s18, s22, 0x10080
	s_addc_u32 s19, s23, 0
	s_add_i32 s22, s53, s28
	global_load_lds_dwordx4 v142, s[100:101]
	s_mov_b32 m0, s22
	s_nop 0
	global_load_lds_dwordx4 v2, s[18:19]
	s_add_i32 m0, s22, 0x2000
	s_nop 0
	global_load_lds_dwordx4 v142, s[18:19]
	s_add_u32 s100, s24, 0x80
	s_addc_u32 s101, s25, 0
	s_mov_b32 m0, s47
	s_nop 0
	global_load_lds_dwordx4 v0, s[100:101]
	s_mov_b32 m0, s48
	s_nop 0
	global_load_lds_dwordx4 v140, s[100:101]
	s_waitcnt vmcnt(8)
	s_waitcnt lgkmcnt(0)
	s_barrier
	s_setprio 1
	s_waitcnt lgkmcnt(0)
	v_mfma_f32_16x16x32_bf16 v[64:67], v[148:151], v[186:189], v[64:67]
	v_mfma_f32_16x16x32_bf16 v[60:63], v[162:165], v[186:189], v[60:63]
	v_mfma_f32_16x16x32_bf16 v[52:55], v[148:151], v[212:215], v[52:55]
	v_mfma_f32_16x16x32_bf16 v[44:47], v[162:165], v[212:215], v[44:47]
	v_mfma_f32_16x16x32_bf16 v[36:39], v[148:151], v[220:223], v[36:39]
	v_mfma_f32_16x16x32_bf16 v[28:31], v[162:165], v[220:223], v[28:31]
	v_mfma_f32_16x16x32_bf16 v[20:23], v[148:151], v[228:231], v[20:23]
	v_mfma_f32_16x16x32_bf16 v[12:15], v[162:165], v[228:231], v[12:15]
	v_mfma_f32_16x16x32_bf16 v[64:67], v[158:161], v[208:211], v[64:67]
	v_mfma_f32_16x16x32_bf16 v[60:63], v[166:169], v[208:211], v[60:63]
	v_mfma_f32_16x16x32_bf16 v[52:55], v[158:161], v[216:219], v[52:55]
	v_mfma_f32_16x16x32_bf16 v[44:47], v[166:169], v[216:219], v[44:47]
	v_mfma_f32_16x16x32_bf16 v[36:39], v[158:161], v[224:227], v[36:39]
	v_mfma_f32_16x16x32_bf16 v[28:31], v[166:169], v[224:227], v[28:31]
	v_mfma_f32_16x16x32_bf16 v[20:23], v[158:161], v[232:235], v[20:23]
	v_mfma_f32_16x16x32_bf16 v[12:15], v[166:169], v[232:235], v[12:15]
	s_setprio 0
	s_add_i32 s51, s51, 2
	s_add_u32 s40, s40, 0x100
	s_addc_u32 s41, s41, 0
	s_add_u32 s42, s42, 0x100
	s_addc_u32 s43, s43, 0
	s_add_u32 s18, s40, 0xfffc0080
	s_addc_u32 s19, s41, -1
	s_add_i32 s52, 0, 0x10000
	s_cmp_eq_u32 s51, 12
	s_cselect_b32 s25, s7, s19
	s_cselect_b32 s24, s13, s18
	s_cselect_b32 s23, s5, s43
	s_cselect_b32 s22, s17, s42
	s_add_i32 s53, 0, 0x14000
	s_setprio 1
	v_mfma_f32_16x16x32_bf16 v[56:59], v[170:173], v[186:189], v[56:59]
	v_mfma_f32_16x16x32_bf16 v[48:51], v[178:181], v[186:189], v[48:51]
	v_mfma_f32_16x16x32_bf16 v[40:43], v[170:173], v[212:215], v[40:43]
	v_mfma_f32_16x16x32_bf16 v[32:35], v[178:181], v[212:215], v[32:35]
	v_mfma_f32_16x16x32_bf16 v[24:27], v[170:173], v[220:223], v[24:27]
	v_mfma_f32_16x16x32_bf16 v[16:19], v[178:181], v[220:223], v[16:19]
	v_mfma_f32_16x16x32_bf16 v[8:11], v[170:173], v[228:231], v[8:11]
	v_mfma_f32_16x16x32_bf16 v[4:7], v[178:181], v[228:231], v[4:7]
	v_mfma_f32_16x16x32_bf16 v[56:59], v[174:177], v[208:211], v[56:59]
	v_mfma_f32_16x16x32_bf16 v[48:51], v[182:185], v[208:211], v[48:51]
	v_mfma_f32_16x16x32_bf16 v[40:43], v[174:177], v[216:219], v[40:43]
	v_mfma_f32_16x16x32_bf16 v[32:35], v[182:185], v[216:219], v[32:35]
	v_mfma_f32_16x16x32_bf16 v[24:27], v[174:177], v[224:227], v[24:27]
	v_mfma_f32_16x16x32_bf16 v[16:19], v[182:185], v[224:227], v[16:19]
	v_mfma_f32_16x16x32_bf16 v[8:11], v[174:177], v[232:235], v[8:11]
	v_mfma_f32_16x16x32_bf16 v[4:7], v[182:185], v[232:235], v[4:7]
	s_setprio 0
	s_barrier
	s_cmp_gt_u32 s51, 13
	s_cbranch_scc0 .Lrot_928
	s_lshl_b32 s5, s16, 8
	s_and_b64 vcc, exec, s[2:3]
	s_cbranch_vccz .LBB0_931
	v_or_b32_e32 v148, s5, v154
	v_ashrrev_i32_e32 v149, 31, v148
	v_lshlrev_b64 v[148:149], 6, v[148:149]
	v_lshl_add_u64 v[166:167], s[74:75], 0, v[148:149]
	global_load_dwordx4 v[148:151], v[166:167], off
	global_load_dwordx4 v[158:161], v[166:167], off offset:32
	global_load_dwordx4 v[162:165], v[166:167], off offset:16
	s_nop 0
	global_load_dwordx4 v[166:169], v[166:167], off offset:48
	s_barrier
